# adds hand-written weight-transpose loop in the setup phase (16B loads, next-item prefetch)
# speedup vs baseline: 1.0039x; 1.0039x over previous
; __device__ __forceinline__ unsigned pk2(float lo, float hi) { const f32x2 v = {lo, hi}; const bf16x2_t b = __builtin_convertvector(v, bf16x2_t); return __builtin_bit_cast(unsigned, b); }
; __device__ __forceinline__ void transpose_item(const float* W, int ldw, int K, bf16_t* WT, int k0, int n0, int drow0, float* scr, int lane) {
; #pragma unroll 8
;     for (int i = 0; i < 32; ++i) { const int kk = 2 * i + (lane >> 5); scr[kk * 33 + (lane & 31)] = W[(size_t)(k0 + kk) * ldw + n0 + (lane & 31)]; }
;     asm volatile("s_waitcnt lgkmcnt(0)" ::: "memory");
;     const int c = lane & 7;
; #pragma unroll
;     for (int j = 0; j < 4; ++j) { const int n = (lane >> 3) + 8 * j; const float* s = scr + (8 * c) * 33 + n;
;         u32x4 o; o.x = pk2(s[0 * 33], s[1 * 33]); o.y = pk2(s[2 * 33], s[3 * 33]); o.z = pk2(s[4 * 33], s[5 * 33]); o.w = pk2(s[6 * 33], s[7 * 33]);
;         *(u32x4*)(WT + (size_t)(drow0 + n) * K + k0 + 8 * c) = o; }
;     asm volatile("s_waitcnt lgkmcnt(0)" ::: "memory");
; }
; __device__ __forceinline__ void phase0(const Args& a, unsigned char* smem, int tid, int lane, int wave) {
;     ...
;     for (int it = gw; it < I_IN + I_A + I_B + I_O; it += NGW) {
;         int r = it;
;         if (r < I_IN) { const int kb = r / 449, nb = r % 449, n0 = nb * 32;
;             const int drow = n0 < 10240 ? n0 : (n0 < 10272 ? 14336 + (n0 - 10240) : n0 - 32);
;             transpose_item(a.w_in, 14368, 2048, WinT, kb * 64, n0, drow, scr, lane); continue; }
;         r -= I_IN;
;         if (r < I_A) { transpose_item(a.w_br_a, 2048, 1024, (bf16_t*)(a.ws + WS_WA), (r >> 6) * 64, (r & 63) * 32, (r & 63) * 32, scr, lane); continue; }
;         r -= I_A;
;         if (r < I_B) { transpose_item(a.w_br_b, 2048, 2048, (bf16_t*)(a.ws + WS_WB), (r >> 6) * 64, (r & 63) * 32, (r & 63) * 32, scr, lane); continue; }
;         r -= I_B;
;         transpose_item(a.w_out, 2048, 2048, (bf16_t*)(a.ws + WS_WO), (r >> 6) * 64, (r & 63) * 32, (r & 63) * 32, scr, lane);
;     }
.LBB0_25:
	s_cmpk_gt_i32 s13, 0x4c1f
	s_cbranch_scc1 .LBB0_48
	v_lshrrev_b32_e32 v1, 3, v160
	v_and_b32_e32 v2, 7, v160
	s_mul_i32 s19, s0, 0x2100
	v_mul_u32_u24_e32 v4, 0x420, v2
	v_lshl_add_u32 v4, v1, 2, v4
	v_add_u32_e32 v4, s19, v4
	v_lshlrev_b32_e32 v2, 4, v2
	v_mul_u32_u24_e32 v3, 0x84, v1
	v_add3_u32 v3, v3, v2, s19
	s_cmp_lt_u32 s13, 14368
	s_cbranch_scc0 .Ltr0_a_k1
	s_mul_hi_u32 s19, s13, 0x91f5bd
	s_mul_i32 s27, s19, 449
	s_sub_i32 s27, s13, s27
	s_lshl_b32 s16, s19, 6
	s_lshl_b32 s17, s27, 5
	s_mov_b64 s[52:53], s[88:89]
	s_mov_b32 s22, 0xe080
	s_branch .Ltr0_a_done
.Ltr0_a_k1:
	s_cmp_lt_u32 s13, 15392
	s_cbranch_scc0 .Ltr0_a_k2
	s_sub_i32 s19, s13, 14368
	s_lshr_b32 s16, s19, 6
	s_lshl_b32 s16, s16, 6
	s_and_b32 s17, s19, 63
	s_lshl_b32 s17, s17, 5
	s_mov_b64 s[52:53], s[66:67]
	s_movk_i32 s22, 0x2000
	s_branch .Ltr0_a_done
.Ltr0_a_k2:
	s_cmp_lt_u32 s13, 17440
	s_cbranch_scc0 .Ltr0_a_k3
	s_sub_i32 s19, s13, 15392
	s_lshr_b32 s16, s19, 6
	s_lshl_b32 s16, s16, 6
	s_and_b32 s17, s19, 63
	s_lshl_b32 s17, s17, 5
	s_mov_b64 s[52:53], s[68:69]
	s_movk_i32 s22, 0x2000
	s_branch .Ltr0_a_done
.Ltr0_a_k3:
	s_sub_i32 s19, s13, 17440
	s_lshr_b32 s16, s19, 6
	s_lshl_b32 s16, s16, 6
	s_and_b32 s17, s19, 63
	s_lshl_b32 s17, s17, 5
	s_mov_b64 s[52:53], s[70:71]
	s_movk_i32 s22, 0x2000
.Ltr0_a_done:
	s_mul_i32 s19, s16, s22
	s_lshl_b32 s27, s17, 2
	s_add_u32 s19, s19, s27
	s_add_u32 s28, s52, s19
	s_addc_u32 s29, s53, 0
	s_lshl_b32 s19, s22, 3
	s_add_u32 s30, s28, s19
	s_addc_u32 s31, s29, 0
	s_add_u32 s32, s30, s19
	s_addc_u32 s33, s31, 0
	s_add_u32 s34, s32, s19
	s_addc_u32 s35, s33, 0
	s_add_u32 s36, s34, s19
	s_addc_u32 s37, s35, 0
	s_add_u32 s38, s36, s19
	s_addc_u32 s39, s37, 0
	s_add_u32 s40, s38, s19
	s_addc_u32 s41, s39, 0
	s_add_u32 s42, s40, s19
	s_addc_u32 s43, s41, 0
	v_mad_u32_u24 v7, v1, s22, v2
	global_load_dwordx4 v[16:19], v7, s[28:29]
	global_load_dwordx4 v[20:23], v7, s[30:31]
	global_load_dwordx4 v[24:27], v7, s[32:33]
	global_load_dwordx4 v[28:31], v7, s[34:35]
	global_load_dwordx4 v[32:35], v7, s[36:37]
	global_load_dwordx4 v[36:39], v7, s[38:39]
	global_load_dwordx4 v[40:43], v7, s[40:41]
	global_load_dwordx4 v[44:47], v7, s[42:43]
	s_waitcnt vmcnt(0)
	s_branch .Ltr0_body
.Ltr0_loop:
	s_waitcnt vmcnt(4)
.Ltr0_body:
	ds_write_b32 v3, v16
	ds_write_b32 v3, v17 offset:4
	ds_write_b32 v3, v18 offset:8
	ds_write_b32 v3, v19 offset:12
	ds_write_b32 v3, v20 offset:1056
	ds_write_b32 v3, v21 offset:1060
	ds_write_b32 v3, v22 offset:1064
	ds_write_b32 v3, v23 offset:1068
	ds_write_b32 v3, v24 offset:2112
	ds_write_b32 v3, v25 offset:2116
	ds_write_b32 v3, v26 offset:2120
	ds_write_b32 v3, v27 offset:2124
	ds_write_b32 v3, v28 offset:3168
	ds_write_b32 v3, v29 offset:3172
	ds_write_b32 v3, v30 offset:3176
	ds_write_b32 v3, v31 offset:3180
	ds_write_b32 v3, v32 offset:4224
	ds_write_b32 v3, v33 offset:4228
	ds_write_b32 v3, v34 offset:4232
	ds_write_b32 v3, v35 offset:4236
	ds_write_b32 v3, v36 offset:5280
	ds_write_b32 v3, v37 offset:5284
	ds_write_b32 v3, v38 offset:5288
	ds_write_b32 v3, v39 offset:5292
	ds_write_b32 v3, v40 offset:6336
	ds_write_b32 v3, v41 offset:6340
	ds_write_b32 v3, v42 offset:6344
	ds_write_b32 v3, v43 offset:6348
	ds_write_b32 v3, v44 offset:7392
	ds_write_b32 v3, v45 offset:7396
	ds_write_b32 v3, v46 offset:7400
	ds_write_b32 v3, v47 offset:7404
	s_add_i32 s15, s13, s14
	s_cmp_lt_u32 s15, 19488
	s_cbranch_scc0 .Ltr0_nopf
	s_cmp_lt_u32 s15, 14368
	s_cbranch_scc0 .Ltr0_b_k1
	s_mul_hi_u32 s19, s15, 0x91f5bd
	s_mul_i32 s27, s19, 449
	s_sub_i32 s27, s15, s27
	s_lshl_b32 s16, s19, 6
	s_lshl_b32 s17, s27, 5
	s_mov_b64 s[52:53], s[88:89]
	s_mov_b32 s22, 0xe080
	s_branch .Ltr0_b_done
.Ltr0_b_k1:
	s_cmp_lt_u32 s15, 15392
	s_cbranch_scc0 .Ltr0_b_k2
	s_sub_i32 s19, s15, 14368
	s_lshr_b32 s16, s19, 6
	s_lshl_b32 s16, s16, 6
	s_and_b32 s17, s19, 63
	s_lshl_b32 s17, s17, 5
	s_mov_b64 s[52:53], s[66:67]
	s_movk_i32 s22, 0x2000
	s_branch .Ltr0_b_done
.Ltr0_b_k2:
	s_cmp_lt_u32 s15, 17440
	s_cbranch_scc0 .Ltr0_b_k3
	s_sub_i32 s19, s15, 15392
	s_lshr_b32 s16, s19, 6
	s_lshl_b32 s16, s16, 6
	s_and_b32 s17, s19, 63
	s_lshl_b32 s17, s17, 5
	s_mov_b64 s[52:53], s[68:69]
	s_movk_i32 s22, 0x2000
	s_branch .Ltr0_b_done
.Ltr0_b_k3:
	s_sub_i32 s19, s15, 17440
	s_lshr_b32 s16, s19, 6
	s_lshl_b32 s16, s16, 6
	s_and_b32 s17, s19, 63
	s_lshl_b32 s17, s17, 5
	s_mov_b64 s[52:53], s[70:71]
	s_movk_i32 s22, 0x2000
; __device__ __forceinline__ unsigned pk2(float lo, float hi) { const f32x2 v = {lo, hi}; const bf16x2_t b = __builtin_convertvector(v, bf16x2_t); return __builtin_bit_cast(unsigned, b); }
; __device__ __forceinline__ void transpose_item(const float* W, int ldw, int K, bf16_t* WT, int k0, int n0, int drow0, float* scr, int lane) {
; #pragma unroll 8
;     for (int i = 0; i < 32; ++i) { const int kk = 2 * i + (lane >> 5); scr[kk * 33 + (lane & 31)] = W[(size_t)(k0 + kk) * ldw + n0 + (lane & 31)]; }
;     asm volatile("s_waitcnt lgkmcnt(0)" ::: "memory");
;     const int c = lane & 7;
; #pragma unroll
;     for (int j = 0; j < 4; ++j) { const int n = (lane >> 3) + 8 * j; const float* s = scr + (8 * c) * 33 + n;
;         u32x4 o; o.x = pk2(s[0 * 33], s[1 * 33]); o.y = pk2(s[2 * 33], s[3 * 33]); o.z = pk2(s[4 * 33], s[5 * 33]); o.w = pk2(s[6 * 33], s[7 * 33]);
;         *(u32x4*)(WT + (size_t)(drow0 + n) * K + k0 + 8 * c) = o; }
;     asm volatile("s_waitcnt lgkmcnt(0)" ::: "memory");
; }
; __device__ __forceinline__ void phase0(const Args& a, unsigned char* smem, int tid, int lane, int wave) {
;     ...
;     for (int it = gw; it < I_IN + I_A + I_B + I_O; it += NGW) {
;         int r = it;
;         if (r < I_IN) { const int kb = r / 449, nb = r % 449, n0 = nb * 32;
;             const int drow = n0 < 10240 ? n0 : (n0 < 10272 ? 14336 + (n0 - 10240) : n0 - 32);
;             transpose_item(a.w_in, 14368, 2048, WinT, kb * 64, n0, drow, scr, lane); continue; }
;         r -= I_IN;
;         if (r < I_A) { transpose_item(a.w_br_a, 2048, 1024, (bf16_t*)(a.ws + WS_WA), (r >> 6) * 64, (r & 63) * 32, (r & 63) * 32, scr, lane); continue; }
;         r -= I_A;
;         if (r < I_B) { transpose_item(a.w_br_b, 2048, 2048, (bf16_t*)(a.ws + WS_WB), (r >> 6) * 64, (r & 63) * 32, (r & 63) * 32, scr, lane); continue; }
;         r -= I_B;
;         transpose_item(a.w_out, 2048, 2048, (bf16_t*)(a.ws + WS_WO), (r >> 6) * 64, (r & 63) * 32, (r & 63) * 32, scr, lane);
;     }
.Ltr0_b_done:
	s_mul_i32 s19, s16, s22
	s_lshl_b32 s27, s17, 2
	s_add_u32 s19, s19, s27
	s_add_u32 s28, s52, s19
	s_addc_u32 s29, s53, 0
	s_lshl_b32 s19, s22, 3
	s_add_u32 s30, s28, s19
	s_addc_u32 s31, s29, 0
	s_add_u32 s32, s30, s19
	s_addc_u32 s33, s31, 0
	s_add_u32 s34, s32, s19
	s_addc_u32 s35, s33, 0
	s_add_u32 s36, s34, s19
	s_addc_u32 s37, s35, 0
	s_add_u32 s38, s36, s19
	s_addc_u32 s39, s37, 0
	s_add_u32 s40, s38, s19
	s_addc_u32 s41, s39, 0
	s_add_u32 s42, s40, s19
	s_addc_u32 s43, s41, 0
	v_mad_u32_u24 v7, v1, s22, v2
	global_load_dwordx4 v[16:19], v7, s[28:29]
	global_load_dwordx4 v[20:23], v7, s[30:31]
	global_load_dwordx4 v[24:27], v7, s[32:33]
	global_load_dwordx4 v[28:31], v7, s[34:35]
	global_load_dwordx4 v[32:35], v7, s[36:37]
	global_load_dwordx4 v[36:39], v7, s[38:39]
	global_load_dwordx4 v[40:43], v7, s[40:41]
	global_load_dwordx4 v[44:47], v7, s[42:43]
.Ltr0_nopf:
	s_cmp_lt_u32 s13, 14368
	s_cbranch_scc0 .Ltr0_c_k1
	s_mul_hi_u32 s19, s13, 0x91f5bd
	s_mul_i32 s27, s19, 449
	s_sub_i32 s27, s13, s27
	s_lshl_b32 s16, s19, 6
	s_lshl_b32 s17, s27, 5
	s_add_i32 s19, s17, 4096
	s_sub_i32 s27, s17, 32
	s_cmp_lt_u32 s17, 10272
	s_cselect_b32 s18, s19, s27
	s_cmp_lt_u32 s17, 10240
	s_cselect_b32 s18, s17, s18
	s_add_u32 s52, s92, 0x8200000
	s_addc_u32 s53, s93, 0
	s_movk_i32 s26, 0x1000
	s_branch .Ltr0_c_done
.Ltr0_c_k1:
	s_cmp_lt_u32 s13, 15392
	s_cbranch_scc0 .Ltr0_c_k2
	s_sub_i32 s19, s13, 14368
	s_lshr_b32 s16, s19, 6
	s_lshl_b32 s16, s16, 6
	s_and_b32 s17, s19, 63
	s_lshl_b32 s17, s17, 5
	s_mov_b32 s18, s17
	s_add_u32 s52, s94, 0x39310000
	s_addc_u32 s53, s95, 0
	s_movk_i32 s26, 0x800
	s_branch .Ltr0_c_done
.Ltr0_c_k2:
	s_cmp_lt_u32 s13, 17440
	s_cbranch_scc0 .Ltr0_c_k3
	s_sub_i32 s19, s13, 15392
	s_lshr_b32 s16, s19, 6
	s_lshl_b32 s16, s16, 6
	s_and_b32 s17, s19, 63
	s_lshl_b32 s17, s17, 5
	s_mov_b32 s18, s17
	s_add_u32 s52, s94, 0x39710000
	s_addc_u32 s53, s95, 0
	s_movk_i32 s26, 0x1000
	s_branch .Ltr0_c_done
.Ltr0_c_k3:
	s_sub_i32 s19, s13, 17440
	s_lshr_b32 s16, s19, 6
	s_lshl_b32 s16, s16, 6
	s_and_b32 s17, s19, 63
	s_lshl_b32 s17, s17, 5
	s_mov_b32 s18, s17
	s_add_u32 s52, s94, 0x39f10000
	s_addc_u32 s53, s95, 0
	s_movk_i32 s26, 0x1000
.Ltr0_c_done:
	s_mul_i32 s19, s18, s26
	s_lshl_b32 s27, s16, 1
	s_add_u32 s19, s19, s27
	s_add_u32 s44, s52, s19
	s_addc_u32 s45, s53, 0
	s_lshl_b32 s19, s26, 3
	s_add_u32 s46, s44, s19
	s_addc_u32 s47, s45, 0
	s_add_u32 s48, s46, s19
	s_addc_u32 s49, s47, 0
	s_add_u32 s50, s48, s19
	s_addc_u32 s51, s49, 0
	v_mad_u32_u24 v5, v1, s26, v2
	s_waitcnt lgkmcnt(0)
	ds_read2_b32 v[48:49], v4 offset0:0 offset1:33
	ds_read2_b32 v[50:51], v4 offset0:66 offset1:99
	ds_read2_b32 v[52:53], v4 offset0:132 offset1:165
	ds_read2_b32 v[54:55], v4 offset0:198 offset1:231
	ds_read2_b32 v[56:57], v4 offset0:8 offset1:41
	ds_read2_b32 v[58:59], v4 offset0:74 offset1:107
	ds_read2_b32 v[60:61], v4 offset0:140 offset1:173
	ds_read2_b32 v[62:63], v4 offset0:206 offset1:239
	s_waitcnt lgkmcnt(7)
	v_cvt_pk_bf16_f32 v96, v48, v49
	s_waitcnt lgkmcnt(6)
	v_cvt_pk_bf16_f32 v97, v50, v51
	s_waitcnt lgkmcnt(5)
	v_cvt_pk_bf16_f32 v98, v52, v53
	s_waitcnt lgkmcnt(4)
	v_cvt_pk_bf16_f32 v99, v54, v55
	global_store_dwordx4 v5, v[96:99], s[44:45]
	s_waitcnt lgkmcnt(3)
	v_cvt_pk_bf16_f32 v100, v56, v57
	s_waitcnt lgkmcnt(2)
	v_cvt_pk_bf16_f32 v101, v58, v59
	s_waitcnt lgkmcnt(1)
	v_cvt_pk_bf16_f32 v102, v60, v61
	s_waitcnt lgkmcnt(0)
	v_cvt_pk_bf16_f32 v103, v62, v63
	global_store_dwordx4 v5, v[100:103], s[46:47]
	ds_read2_b32 v[64:65], v4 offset0:16 offset1:49
	ds_read2_b32 v[66:67], v4 offset0:82 offset1:115
	ds_read2_b32 v[68:69], v4 offset0:148 offset1:181
	ds_read2_b32 v[70:71], v4 offset0:214 offset1:247
	ds_read2_b32 v[72:73], v4 offset0:24 offset1:57
	ds_read2_b32 v[74:75], v4 offset0:90 offset1:123
	ds_read2_b32 v[76:77], v4 offset0:156 offset1:189
	ds_read2_b32 v[78:79], v4 offset0:222 offset1:255
	s_waitcnt lgkmcnt(7)
	v_cvt_pk_bf16_f32 v104, v64, v65
	s_waitcnt lgkmcnt(6)
	v_cvt_pk_bf16_f32 v105, v66, v67
	s_waitcnt lgkmcnt(5)
	v_cvt_pk_bf16_f32 v106, v68, v69
	s_waitcnt lgkmcnt(4)
	v_cvt_pk_bf16_f32 v107, v70, v71
	global_store_dwordx4 v5, v[104:107], s[48:49]
	s_waitcnt lgkmcnt(3)
	v_cvt_pk_bf16_f32 v108, v72, v73
	s_waitcnt lgkmcnt(2)
	v_cvt_pk_bf16_f32 v109, v74, v75
	s_waitcnt lgkmcnt(1)
	v_cvt_pk_bf16_f32 v110, v76, v77
	s_waitcnt lgkmcnt(0)
	v_cvt_pk_bf16_f32 v111, v78, v79
	global_store_dwordx4 v5, v[108:111], s[50:51]
	s_mov_b32 s13, s15
	s_cmp_lt_u32 s13, 19488
	s_cbranch_scc1 .Ltr0_loop
	s_waitcnt lgkmcnt(0)
